# attention: touch next unit's first K/V tiles and Q rows into L2 during the tail
# speedup vs baseline: 1.0098x; 1.0032x over previous
; #define DMA_TILE(t, ks, vs) do { glds16(ksrc + (long)(t) * KVBLK * KNP, (unsigned)__builtin_amdgcn_readfirstlane(kdst + (ks) * KSLOT)); \
;         glds16(k2src + (long)(t) * KVBLK * KPP, (unsigned)__builtin_amdgcn_readfirstlane(k2dst + (ks) * KSLOT)); \
;         glds16(vsrc + (long)(t) * KVBLK * VP, (unsigned)__builtin_amdgcn_readfirstlane(vdst + (vs) * VSLOT)); } while (0)
; #define V_LOAD(vs) do { const LAS char* vp_ = vp0 + (vs) * VSLOT; \
;         _Pragma("unroll") for (int i_ = 0; i_ < 8; ++i_) { vlo[i_] = vtr(vp_ + ((i_ >> 2) * 4096 + (i_ & 3) * 1024)); vhi[i_] = vtr(vp_ + ((i_ >> 2) * 4096 + (i_ & 3) * 1024 + 512)); } SBAR(); } while (0)
; __device__ __forceinline__ void attn_unit(int b, int h, int qb, const bf16* Q, const bf16* __restrict__ Kn, const bf16* __restrict__ Kpe, const bf16* __restrict__ V, bf16* O, float* ASS, LAS char* shm) {
;     ...
;     const bf16* ksrc = Kn + (rowbase + lane) * KNP + h * 64 + wid * 8;
;     const bf16* k2src = Kpe + (rowbase + lane) * KPP + (wid & 3) * 8;
;     const bf16* vsrc = V + (rowbase + 16 * (wid & 3) + (lane >> 2)) * VP + h * 64 + (wid >> 2) * 32 + (lane & 3) * 8;
;     const unsigned kdst = lds0 + LDS_K + wid * 1024, k2dst = lds0 + LDS_K + (8 + (wid & 3)) * 1024, vdst = lds0 + LDS_V + wid * 1024;
;     ...
;     const int vb0 = (int)(lds0 + LDS_V) + ((lane >> 4) & 1) * 32 + (lane & 3) * 8 + (4 * hi + ((lane & 15) >> 2)) * 64;
;     const int NT = (q0 + QB) / KVBLK;
;     DMA_TILE(0, 0, 0); DMA_TILE(1, 1, 1);
;     bf16x8 qr[6];
; #pragma unroll
;     for (int d0 = 0; d0 < 6; ++d0) qr[d0] = *reinterpret_cast<const bf16x8*>(&Qw[(long)r32 * QP + d0 * 16 + hi * 8]);
;     ...
;         V_LOAD((vs + 3) & 3);
;         SOFTMAX();
;         PV_MMA();
.Lat_u1_tail:
	s_add_u32 s4, s86, 2
	s_lshl_b32 s5, s4, 16
	s_sub_u32 s5, 0, s5
	s_mov_b32 s53, -1
	s_mov_b32 vcc_lo, s5
	s_mov_b32 vcc_hi, s53
	v_lshl_add_u64 v[168:169], v[126:127], 0, vcc
	global_load_dword v155, v[168:169], off
	v_lshl_add_u64 v[168:169], v[168:169], 0, s[34:35]
	global_load_dword v155, v[168:169], off
	v_lshl_add_u64 v[168:169], v[124:125], 0, vcc
	global_load_dword v155, v[168:169], off
	v_lshl_add_u64 v[168:169], v[168:169], 0, s[34:35]
	global_load_dword v155, v[168:169], off
	s_lshl_b32 s5, s4, 12
	s_sub_u32 s5, 0, s5
	s_mov_b32 vcc_lo, s5
	v_lshl_add_u64 v[168:169], v[14:15], 0, vcc
	global_load_dword v155, v[168:169], off
	v_lshl_add_u64 v[168:169], v[168:169], 0, s[20:21]
	global_load_dword v155, v[168:169], off
	s_lshl_b32 s4, s69, 5
	s_add_u32 s4, s4, s88
	s_mul_i32 s4, s4, 0x600
	s_add_u32 s4, s4, s64
	s_add_u32 s4, s4, s78
	s_addc_u32 s5, s79, 0
	v_mul_u32_u24_e32 v172, 0x600, v140
	global_load_dword v155, v172, s[4:5]
	global_load_dword v155, v172, s[4:5] offset:64
	global_load_dword v155, v172, s[4:5] offset:128
	s_waitcnt lgkmcnt(0)
	s_lshr_b32 s4, s69, 1
	s_sub_u32 s4, s52, s4
	s_sub_u32 s4, s4, 1
	s_cmp_gt_i32 s4, s87
	s_cbranch_scc1 .Lat_u1t_skip
	s_lshl_b32 s4, s50, 13
	s_add_i32 s4, s4, 0x6000
	s_and_b32 s4, s4, 0x6000
	v_add_u32_e32 v159, s4, v144
	ds_read_b64_tr_b16 v[196:197], v159 offset:36864
	ds_read_b64_tr_b16 v[198:199], v159 offset:37376
	ds_read_b64_tr_b16 v[200:201], v159 offset:37888
	ds_read_b64_tr_b16 v[202:203], v159 offset:38400
	ds_read_b64_tr_b16 v[204:205], v159 offset:38912
	ds_read_b64_tr_b16 v[206:207], v159 offset:39424
	ds_read_b64_tr_b16 v[208:209], v159 offset:39936
	ds_read_b64_tr_b16 v[210:211], v159 offset:40448
	ds_read_b64_tr_b16 v[212:213], v159 offset:40960
	ds_read_b64_tr_b16 v[214:215], v159 offset:41472
	ds_read_b64_tr_b16 v[230:231], v159 offset:41984
	ds_read_b64_tr_b16 v[232:233], v159 offset:42496
	ds_read_b64_tr_b16 v[234:235], v159 offset:43008
	ds_read_b64_tr_b16 v[236:237], v159 offset:43520
	ds_read_b64_tr_b16 v[164:165], v159 offset:44032
	ds_read_b64_tr_b16 v[166:167], v159 offset:44544
	v_mov_b32_e32 v156, 0
	v_mov_b32_e32 v157, 0
	v_exp_f32_e32 v238, v238
	v_exp_f32_e32 v239, v239
	v_add_f32_e32 v156, v156, v238
	v_add_f32_e32 v156, v156, v239
	v_cvt_pk_bf16_f32 v238, v238, v239
	v_exp_f32_e32 v240, v240
	v_exp_f32_e32 v241, v241
	v_add_f32_e32 v157, v157, v240
	v_add_f32_e32 v157, v157, v241
	v_cvt_pk_bf16_f32 v239, v240, v241
	v_exp_f32_e32 v242, v242
	v_exp_f32_e32 v243, v243
	v_add_f32_e32 v156, v156, v242
	v_add_f32_e32 v156, v156, v243
	v_cvt_pk_bf16_f32 v240, v242, v243
	v_exp_f32_e32 v244, v244
	v_exp_f32_e32 v245, v245
	v_add_f32_e32 v157, v157, v244
	v_add_f32_e32 v157, v157, v245
	v_cvt_pk_bf16_f32 v241, v244, v245
	v_exp_f32_e32 v246, v246
	v_exp_f32_e32 v247, v247
	v_add_f32_e32 v156, v156, v246
	v_add_f32_e32 v156, v156, v247
	v_cvt_pk_bf16_f32 v242, v246, v247
	v_exp_f32_e32 v248, v248
	v_exp_f32_e32 v249, v249
	v_add_f32_e32 v157, v157, v248
	v_add_f32_e32 v157, v157, v249
	v_cvt_pk_bf16_f32 v243, v248, v249
	v_exp_f32_e32 v250, v250
	v_exp_f32_e32 v251, v251
	v_add_f32_e32 v156, v156, v250
	v_add_f32_e32 v156, v156, v251
	v_cvt_pk_bf16_f32 v244, v250, v251
	v_exp_f32_e32 v252, v252
	v_exp_f32_e32 v253, v253
	v_add_f32_e32 v157, v157, v252
	v_add_f32_e32 v157, v157, v253
	v_cvt_pk_bf16_f32 v245, v252, v253
	v_exp_f32_e32 v180, v180
	v_exp_f32_e32 v181, v181
	v_add_f32_e32 v156, v156, v180
	v_add_f32_e32 v156, v156, v181
	v_cvt_pk_bf16_f32 v180, v180, v181
	v_exp_f32_e32 v182, v182
	v_exp_f32_e32 v183, v183
	v_add_f32_e32 v157, v157, v182
	v_add_f32_e32 v157, v157, v183
	v_cvt_pk_bf16_f32 v181, v182, v183
	v_exp_f32_e32 v184, v184
	v_exp_f32_e32 v185, v185
	v_add_f32_e32 v156, v156, v184
	v_add_f32_e32 v156, v156, v185
	v_cvt_pk_bf16_f32 v182, v184, v185
	v_exp_f32_e32 v186, v186
	v_exp_f32_e32 v187, v187
	v_add_f32_e32 v157, v157, v186
	v_add_f32_e32 v157, v157, v187
	v_cvt_pk_bf16_f32 v183, v186, v187
	v_exp_f32_e32 v188, v188
	v_exp_f32_e32 v189, v189
	v_add_f32_e32 v156, v156, v188
	v_add_f32_e32 v156, v156, v189
	v_cvt_pk_bf16_f32 v184, v188, v189
	v_exp_f32_e32 v190, v190
	v_exp_f32_e32 v191, v191
	v_add_f32_e32 v157, v157, v190
	v_add_f32_e32 v157, v157, v191
	v_cvt_pk_bf16_f32 v185, v190, v191
	v_exp_f32_e32 v192, v192
	v_exp_f32_e32 v193, v193
	v_add_f32_e32 v156, v156, v192
	v_add_f32_e32 v156, v156, v193
	v_cvt_pk_bf16_f32 v186, v192, v193
	v_exp_f32_e32 v194, v194
	v_exp_f32_e32 v195, v195
	v_add_f32_e32 v157, v157, v194
	v_add_f32_e32 v157, v157, v195
	v_cvt_pk_bf16_f32 v187, v194, v195
	v_add_f32_e32 v156, v156, v157
	v_add_f32_e32 v128, v128, v156
	s_waitcnt lgkmcnt(0)
	v_mfma_f32_32x32x16_bf16 v[16:31], v[196:199], v[238:241], v[16:31]
	v_mfma_f32_32x32x16_bf16 v[32:47], v[212:215], v[238:241], v[32:47]
	v_mfma_f32_32x32x16_bf16 v[16:31], v[200:203], v[242:245], v[16:31]
	v_mfma_f32_32x32x16_bf16 v[32:47], v[230:233], v[242:245], v[32:47]
	v_mfma_f32_32x32x16_bf16 v[16:31], v[204:207], v[180:183], v[16:31]
	v_mfma_f32_32x32x16_bf16 v[32:47], v[234:237], v[180:183], v[32:47]
	v_mfma_f32_32x32x16_bf16 v[16:31], v[208:211], v[184:187], v[16:31]
	v_mfma_f32_32x32x16_bf16 v[32:47], v[164:167], v[184:187], v[32:47]

; #define DMA_TILE(t, ks, vs) do { glds16(ksrc + (long)(t) * KVBLK * KNP, (unsigned)__builtin_amdgcn_readfirstlane(kdst + (ks) * KSLOT)); \
;         glds16(k2src + (long)(t) * KVBLK * KPP, (unsigned)__builtin_amdgcn_readfirstlane(k2dst + (ks) * KSLOT)); \
;         glds16(vsrc + (long)(t) * KVBLK * VP, (unsigned)__builtin_amdgcn_readfirstlane(vdst + (vs) * VSLOT)); } while (0)
; __device__ __forceinline__ void attn_unit(int b, int h, int qb, const bf16* Q, const bf16* __restrict__ Kn, const bf16* __restrict__ Kpe, const bf16* __restrict__ V, bf16* O, float* ASS, LAS char* shm) {
;     ...
;     const bf16* ksrc = Kn + (rowbase + lane) * KNP + h * 64 + wid * 8;
;     const bf16* k2src = Kpe + (rowbase + lane) * KPP + (wid & 3) * 8;
;     const bf16* vsrc = V + (rowbase + 16 * (wid & 3) + (lane >> 2)) * VP + h * 64 + (wid >> 2) * 32 + (lane & 3) * 8;
;     const unsigned kdst = lds0 + LDS_K + wid * 1024, k2dst = lds0 + LDS_K + (8 + (wid & 3)) * 1024, vdst = lds0 + LDS_V + wid * 1024;
;     ...
;     const int vb0 = (int)(lds0 + LDS_V) + ((lane >> 4) & 1) * 32 + (lane & 3) * 8 + (4 * hi + ((lane & 15) >> 2)) * 64;
;     const int NT = (q0 + QB) / KVBLK;
;     DMA_TILE(0, 0, 0); DMA_TILE(1, 1, 1);
;     bf16x8 qr[6];
; #pragma unroll
;     for (int d0 = 0; d0 < 6; ++d0) qr[d0] = *reinterpret_cast<const bf16x8*>(&Qw[(long)r32 * QP + d0 * 16 + hi * 8]);
.Lat_u2_tail:
	s_cmp_eq_u64 s[70:71], 0
	s_cbranch_scc1 .Lat_u2_nowarm
	s_add_u32 s4, s90, 2
	s_lshl_b32 s5, s4, 16
	s_sub_u32 s5, 0, s5
	s_mov_b32 s63, -1
	s_mov_b32 vcc_lo, s5
	s_mov_b32 vcc_hi, s63
	v_lshl_add_u64 v[168:169], v[126:127], 0, vcc
	global_load_dword v155, v[168:169], off offset:512
	v_lshl_add_u64 v[168:169], v[168:169], 0, s[34:35]
	global_load_dword v155, v[168:169], off offset:512
	v_lshl_add_u64 v[168:169], v[124:125], 0, vcc
	global_load_dword v155, v[168:169], off offset:512
	v_lshl_add_u64 v[168:169], v[168:169], 0, s[34:35]
	global_load_dword v155, v[168:169], off offset:512
	s_lshl_b32 s5, s4, 12
	s_sub_u32 s5, 0, s5
	s_mov_b32 vcc_lo, s5
	v_lshl_add_u64 v[168:169], v[122:123], 0, vcc
	global_load_dword v155, v[168:169], off
	v_lshl_add_u64 v[168:169], v[168:169], 0, s[20:21]
	global_load_dword v155, v[168:169], off
	s_lshl_b32 s4, s56, 5
	s_add_u32 s4, s4, s84
	s_mul_i32 s4, s4, 0x600
	s_add_u32 s4, s4, s64
	s_add_u32 s4, s4, 0x300
	s_add_u32 s4, s4, s78
	s_addc_u32 s5, s79, 0
	v_mul_u32_u24_e32 v172, 0x600, v141
	global_load_dword v155, v172, s[4:5]
	global_load_dword v155, v172, s[4:5] offset:64
	global_load_dword v155, v172, s[4:5] offset:128
